# k35: all sound edits stacked (k31) + counter barrier instead of cg grid.sync + hot loop heads re-aligned to 64 B
# baseline (speedup 1.0000x reference)
; #define PG8_STAGE(bufoff, gbase, voff) do { _Pragma("unroll") for (int _i = 0; _i < 2; ++_i) \
;         __builtin_amdgcn_global_load_lds((const unsigned*)((const char*)(gbase) + (voff)[_i]), (LAS unsigned*)(lds + (bufoff) + ldsw + _i * 8192), 16, 0, 0); } while (0)
; template <class Epi>
; __device__ __forceinline__ void gemm_phase(LAS unsigned char* lds, const Gemm g, const Epi& E) {
;     ...
;     Unit cur, nxt; int ui = 0;
;     if (!S.next(0, cur)) return;
;     f32x4 acc[2][2][4][2];
; #pragma unroll
;     for (int a = 0; a < 2; ++a)
; #pragma unroll
;         for (int b = 0; b < 2; ++b)
; #pragma unroll
;             for (int m = 0; m < 4; ++m)
; #pragma unroll
;                 for (int n = 0; n < 2; ++n) acc[a][b][m][n] = (f32x4){0.f, 0.f, 0.f, 0.f};
;     bf16x8 At[4][2], B0[2][2], B1[2][2];
;     const char* cA = (const char*)g.A + (size_t)g.mapA.src(cur.pm) * tstepA + (size_t)cur.pn * g.a_pn_step;
;     const char* cB = (const char*)g.Bt + (size_t)g.mapB.src(cur.pn) * tstepB;
;     PG8_STAGE(PG8_SB(0, 0), cB, voffB); PG8_STAGE(PG8_SA(0, 0), cA, voffA); PG8_STAGE(PG8_SB(0, 1), cB + hstepB, voffB); PG8_STAGE(PG8_SA(0, 1), cA + hstepA, voffA);
.LBB0_295:
	s_lshl_b64 s[0:1], s[8:9], 17
	v_mov_b64_e32 v[2:3], s[76:77]
	s_add_u32 s5, s91, s0
	v_cmp_lt_i64_e32 vcc, s[12:13], v[2:3]
	s_addc_u32 s9, s25, s1
	s_and_b64 s[0:1], vcc, exec
	v_mov_b32_e32 v2, 0
	s_cselect_b32 s13, s9, s15
	s_cselect_b32 s12, s5, s14
	s_mov_b32 s5, 0
	s_mov_b64 s[28:29], -1
	s_mov_b64 s[58:59], 0
	v_mov_b32_e32 v3, v2
	v_mov_b64_e32 v[4:5], v[2:3]
	v_mov_b64_e32 v[6:7], v[2:3]
	v_mov_b64_e32 v[8:9], v[2:3]
	v_mov_b64_e32 v[10:11], v[2:3]
	v_mov_b64_e32 v[12:13], v[2:3]
	v_mov_b64_e32 v[14:15], v[2:3]
	v_mov_b64_e32 v[16:17], v[2:3]
	v_mov_b64_e32 v[18:19], v[2:3]
	v_mov_b64_e32 v[20:21], v[2:3]
	v_mov_b64_e32 v[22:23], v[2:3]
	v_mov_b64_e32 v[24:25], v[2:3]
	v_mov_b64_e32 v[26:27], v[2:3]
	v_mov_b64_e32 v[28:29], v[2:3]
	v_mov_b64_e32 v[30:31], v[2:3]
	v_mov_b64_e32 v[32:33], v[2:3]
	v_mov_b64_e32 v[34:35], v[2:3]
	v_mov_b64_e32 v[36:37], v[2:3]
	v_mov_b64_e32 v[38:39], v[2:3]
	v_mov_b64_e32 v[40:41], v[2:3]
	v_mov_b64_e32 v[42:43], v[2:3]
	v_mov_b64_e32 v[44:45], v[2:3]
	v_mov_b64_e32 v[46:47], v[2:3]
	v_mov_b64_e32 v[48:49], v[2:3]
	v_mov_b64_e32 v[50:51], v[2:3]
	v_mov_b64_e32 v[52:53], v[2:3]
	v_mov_b64_e32 v[54:55], v[2:3]
	v_mov_b64_e32 v[56:57], v[2:3]
	v_mov_b64_e32 v[58:59], v[2:3]
	v_mov_b64_e32 v[60:61], v[2:3]
	v_mov_b64_e32 v[62:63], v[2:3]
	v_mov_b64_e32 v[64:65], v[2:3]
	v_mov_b64_e32 v[66:67], v[2:3]
	v_mov_b64_e32 v[68:69], v[2:3]
	v_mov_b64_e32 v[70:71], v[2:3]
	v_mov_b64_e32 v[72:73], v[2:3]
	v_mov_b64_e32 v[74:75], v[2:3]
	v_mov_b64_e32 v[76:77], v[2:3]
	v_mov_b64_e32 v[78:79], v[2:3]
	v_mov_b64_e32 v[80:81], v[2:3]
	v_mov_b64_e32 v[82:83], v[2:3]
	v_mov_b64_e32 v[84:85], v[2:3]
	v_mov_b64_e32 v[86:87], v[2:3]
	v_mov_b64_e32 v[88:89], v[2:3]
	v_mov_b64_e32 v[90:91], v[2:3]
	v_mov_b64_e32 v[92:93], v[2:3]
	v_mov_b64_e32 v[94:95], v[2:3]
	v_mov_b64_e32 v[96:97], v[2:3]
	v_mov_b64_e32 v[98:99], v[2:3]
	v_mov_b64_e32 v[100:101], v[2:3]
	v_mov_b64_e32 v[102:103], v[2:3]
	v_mov_b64_e32 v[104:105], v[2:3]
	v_mov_b64_e32 v[106:107], v[2:3]
	v_mov_b64_e32 v[108:109], v[2:3]
	v_mov_b64_e32 v[110:111], v[2:3]
	v_mov_b64_e32 v[112:113], v[2:3]
	v_mov_b64_e32 v[114:115], v[2:3]
	v_mov_b64_e32 v[116:117], v[2:3]
	v_mov_b64_e32 v[118:119], v[2:3]
	v_mov_b64_e32 v[120:121], v[2:3]
	v_mov_b64_e32 v[122:123], v[2:3]
	v_mov_b64_e32 v[124:125], v[2:3]
	v_mov_b64_e32 v[126:127], v[2:3]
	v_mov_b64_e32 v[128:129], v[2:3]
	s_nop 0
	s_nop 0
	s_nop 0
	s_nop 0
	s_nop 0
	s_nop 0
	s_nop 0
	s_nop 0

; #define PG8_STAGE(bufoff, gbase, voff) do { _Pragma("unroll") for (int _i = 0; _i < 2; ++_i) \
;         __builtin_amdgcn_global_load_lds((const unsigned*)((const char*)(gbase) + (voff)[_i]), (LAS unsigned*)(lds + (bufoff) + ldsw + _i * 8192), 16, 0, 0); } while (0)
; #define PG8_LDA(dst, b, h) do { _Pragma("unroll") for (int m = 0; m < 4; ++m) _Pragma("unroll") for (int k = 0; k < 2; ++k) dst[m][k] = *(const LAS bf16x8*)(lds + PG8_SA(b, h) + aoff + m * 2048 + k * 1024); } while (0)
; #define PG8_LDB(dst, b, h) do { _Pragma("unroll") for (int n = 0; n < 2; ++n) _Pragma("unroll") for (int k = 0; k < 2; ++k) dst[n][k] = *(const LAS bf16x8*)(lds + PG8_SB(b, h) + boff + n * 2048 + k * 1024); } while (0)
; #define PG8_MMA(ai, bj, At, Bt) do { __builtin_amdgcn_s_setprio(1); _Pragma("unroll") for (int m = 0; m < 4; ++m) _Pragma("unroll") for (int n = 0; n < 2; ++n) _Pragma("unroll") for (int k = 0; k < 2; ++k) \
;         acc[ai][bj][m][n] = __builtin_amdgcn_mfma_f32_16x16x32_bf16(Bt[n][k], At[m][k], acc[ai][bj][m][n], 0, 0, 0); __builtin_amdgcn_s_setprio(0); } while (0)
; #define PG8_WAIT_L(n) asm volatile("s_waitcnt lgkmcnt(" #n ")" ::: "memory")
; #define PG8_BAR __builtin_amdgcn_s_barrier()
; #define PG8_SCHED __builtin_amdgcn_sched_barrier(0)
; template <class Epi>
; __device__ __forceinline__ void gemm_phase(LAS unsigned char* lds, const Gemm g, const Epi& E) {
;     ...
;         for (int t = 0; t < nt; t += 2) {
;             const bool last = (t == nt - 2);
;             const char* a1 = cA + (size_t)(t + 1) * kstep;
;             const char* a2 = last ? nA : cA + (size_t)(t + 2) * kstep; const char* b2 = last ? nB : cB + (size_t)(t + 2) * kstep;
;             const char* a3 = a2 + kstep; const char* b3 = b2 + kstep;
;             PG8_LDB(B0, 0, 0); PG8_SCHED; PG8_LDA(At, 0, 0); PG8_STAGE(PG8_SA(1, 1), a1 + hstepA, voffA);
;             PG8_WAIT_L(8); PG8_BAR; PG8_WAIT_L(0); PG8_MMA(0, 0, At, B0); PG8_BAR; PG8_SCHED;
;             PG8_LDB(B1, 0, 1); PG8_STAGE(PG8_SB(0, 0), b2, voffB);
;             PG8_BAR; PG8_WAIT_L(0); PG8_MMA(0, 1, At, B1); PG8_BAR;
;             PG8_LDA(At, 0, 1); PG8_STAGE(PG8_SA(0, 0), a2, voffA);
;             PG8_BAR; PG8_WAIT_L(0); PG8_MMA(1, 0, At, B0); PG8_BAR; PG8_SCHED;
.LBB0_330:
	s_ashr_i32 s15, s14, 31
	s_lshl_b64 s[52:53], s[14:15], 19
	s_add_u32 s15, s92, s52
	s_addc_u32 s52, s93, s53
	s_and_b64 s[4:5], s[4:5], exec
	s_cselect_b32 s59, s52, s65
	s_cselect_b32 s58, s15, s64
	s_add_u32 s4, s60, 0x40080
	s_addc_u32 s5, s61, 0
	s_add_u32 s15, s64, 0x100
	v_mov_b32_e32 v2, 0
	s_addc_u32 s52, s65, 0
	s_mov_b32 s53, -2
	v_mov_b32_e32 v3, v2
	v_mov_b64_e32 v[4:5], v[2:3]
	v_mov_b64_e32 v[6:7], v[2:3]
	v_mov_b64_e32 v[8:9], v[2:3]
	v_mov_b64_e32 v[10:11], v[2:3]
	v_mov_b64_e32 v[12:13], v[2:3]
	v_mov_b64_e32 v[14:15], v[2:3]
	v_mov_b64_e32 v[16:17], v[2:3]
	v_mov_b64_e32 v[18:19], v[2:3]
	v_mov_b64_e32 v[20:21], v[2:3]
	v_mov_b64_e32 v[22:23], v[2:3]
	v_mov_b64_e32 v[24:25], v[2:3]
	v_mov_b64_e32 v[26:27], v[2:3]
	v_mov_b64_e32 v[28:29], v[2:3]
	v_mov_b64_e32 v[30:31], v[2:3]
	v_mov_b64_e32 v[32:33], v[2:3]
	v_mov_b64_e32 v[34:35], v[2:3]
	v_mov_b64_e32 v[36:37], v[2:3]
	v_mov_b64_e32 v[38:39], v[2:3]
	v_mov_b64_e32 v[40:41], v[2:3]
	v_mov_b64_e32 v[42:43], v[2:3]
	v_mov_b64_e32 v[44:45], v[2:3]
	v_mov_b64_e32 v[46:47], v[2:3]
	v_mov_b64_e32 v[48:49], v[2:3]
	v_mov_b64_e32 v[50:51], v[2:3]
	v_mov_b64_e32 v[52:53], v[2:3]
	v_mov_b64_e32 v[54:55], v[2:3]
	v_mov_b64_e32 v[56:57], v[2:3]
	v_mov_b64_e32 v[58:59], v[2:3]
	v_mov_b64_e32 v[60:61], v[2:3]
	v_mov_b64_e32 v[62:63], v[2:3]
	v_mov_b64_e32 v[64:65], v[2:3]
	v_mov_b64_e32 v[66:67], v[2:3]
	v_mov_b64_e32 v[68:69], v[2:3]
	v_mov_b64_e32 v[70:71], v[2:3]
	v_mov_b64_e32 v[72:73], v[2:3]
	v_mov_b64_e32 v[78:79], v[2:3]
	v_mov_b64_e32 v[80:81], v[2:3]
	v_mov_b64_e32 v[90:91], v[2:3]
	v_mov_b64_e32 v[92:93], v[2:3]
	v_mov_b64_e32 v[98:99], v[2:3]
	v_mov_b64_e32 v[100:101], v[2:3]
	v_mov_b64_e32 v[102:103], v[2:3]
	v_mov_b64_e32 v[104:105], v[2:3]
	v_mov_b64_e32 v[114:115], v[2:3]
	v_mov_b64_e32 v[116:117], v[2:3]
	v_mov_b64_e32 v[118:119], v[2:3]
	v_mov_b64_e32 v[120:121], v[2:3]
	v_mov_b64_e32 v[122:123], v[2:3]
	v_mov_b64_e32 v[124:125], v[2:3]
	v_mov_b64_e32 v[126:127], v[2:3]
	v_mov_b64_e32 v[128:129], v[2:3]
	v_mov_b64_e32 v[138:139], v[2:3]
	v_mov_b64_e32 v[140:141], v[2:3]
	v_mov_b64_e32 v[142:143], v[2:3]
	v_mov_b64_e32 v[144:145], v[2:3]
	v_mov_b64_e32 v[146:147], v[2:3]
	v_mov_b64_e32 v[148:149], v[2:3]
	v_mov_b64_e32 v[150:151], v[2:3]
	v_mov_b64_e32 v[152:153], v[2:3]
	v_mov_b64_e32 v[162:163], v[2:3]
	v_mov_b64_e32 v[164:165], v[2:3]
	v_mov_b64_e32 v[166:167], v[2:3]
	v_mov_b64_e32 v[168:169], v[2:3]
	s_nop 0
	s_nop 0
.LBB0_331:
	s_add_u32 s60, s4, 0xfffc0080
	s_addc_u32 s61, s5, -1
	s_add_i32 s72, 0, 0x10000
	v_add_u32_e32 v94, s72, v201
	ds_read_b128 v[74:77], v94
	ds_read_b128 v[82:85], v94 offset:1024
	ds_read_b128 v[86:89], v94 offset:2048
	ds_read_b128 v[94:97], v94 offset:3072
	s_cmp_eq_u32 s53, 12
	s_cselect_b32 s65, s29, s61
	s_cselect_b32 s64, s28, s60
	s_cselect_b32 s61, s59, s52
	s_cselect_b32 s60, s58, s15
	v_lshl_add_u64 v[192:193], s[4:5], 0, v[188:189]
	s_add_i32 m0, s24, 0xc000
	ds_read_b128 v[106:109], v202
	ds_read_b128 v[110:113], v202 offset:1024
	ds_read_b128 v[130:133], v202 offset:2048
	ds_read_b128 v[134:137], v202 offset:3072
	ds_read_b128 v[154:157], v202 offset:4096
	ds_read_b128 v[158:161], v202 offset:5120
	ds_read_b128 v[170:173], v202 offset:6144
	ds_read_b128 v[174:177], v202 offset:7168
	global_load_lds_dwordx4 v[192:193], off
	v_lshl_add_u64 v[192:193], s[4:5], 0, v[190:191]
	s_add_i32 m0, s24, 0xe000
	s_nop 0
	global_load_lds_dwordx4 v[192:193], off
	s_waitcnt lgkmcnt(8)
	s_barrier
	s_waitcnt lgkmcnt(0)
	v_mfma_f32_16x16x32_bf16 v[166:169], v[74:77], v[106:109], v[166:169]
	v_mfma_f32_16x16x32_bf16 v[162:165], v[86:89], v[106:109], v[162:165]
	v_mfma_f32_16x16x32_bf16 v[142:145], v[74:77], v[130:133], v[142:145]
	v_mfma_f32_16x16x32_bf16 v[138:141], v[86:89], v[130:133], v[138:141]
	v_mfma_f32_16x16x32_bf16 v[118:121], v[74:77], v[154:157], v[118:121]
	v_mfma_f32_16x16x32_bf16 v[114:117], v[86:89], v[154:157], v[114:117]
	v_mfma_f32_16x16x32_bf16 v[90:93], v[74:77], v[170:173], v[90:93]
	v_mfma_f32_16x16x32_bf16 v[78:81], v[86:89], v[170:173], v[78:81]
	v_mfma_f32_16x16x32_bf16 v[166:169], v[82:85], v[110:113], v[166:169]
	v_mfma_f32_16x16x32_bf16 v[162:165], v[94:97], v[110:113], v[162:165]
	v_mfma_f32_16x16x32_bf16 v[142:145], v[82:85], v[134:137], v[142:145]
	v_mfma_f32_16x16x32_bf16 v[138:141], v[94:97], v[134:137], v[138:141]
	v_mfma_f32_16x16x32_bf16 v[118:121], v[82:85], v[158:161], v[118:121]
	v_mfma_f32_16x16x32_bf16 v[114:117], v[94:97], v[158:161], v[114:117]
	v_mfma_f32_16x16x32_bf16 v[90:93], v[82:85], v[174:177], v[90:93]
	v_mfma_f32_16x16x32_bf16 v[78:81], v[94:97], v[174:177], v[78:81]
	s_barrier
	s_add_i32 s74, 0, 0x14000
	s_add_i32 s72, s72, s1
	v_add_u32_e32 v203, s74, v201
	v_lshl_add_u64 v[208:209], s[60:61], 0, v[184:185]
	s_mov_b32 m0, s72
	ds_read_b128 v[192:195], v203
	ds_read_b128 v[196:199], v203 offset:1024
	ds_read_b128 v[204:207], v203 offset:2048
	ds_read_b128 v[226:229], v203 offset:3072
	global_load_lds_dwordx4 v[208:209], off
	v_lshl_add_u64 v[234:235], s[60:61], 0, v[180:181]
	s_add_i32 m0, s72, 0x2000
	s_nop 0
	global_load_lds_dwordx4 v[234:235], off
	s_nop 1
	s_mov_b32 m0, s24
	v_lshl_add_u64 v[236:237], s[64:65], 0, v[186:187]
	s_barrier
; #define PG8_STAGE(bufoff, gbase, voff) do { _Pragma("unroll") for (int _i = 0; _i < 2; ++_i) \
;         __builtin_amdgcn_global_load_lds((const unsigned*)((const char*)(gbase) + (voff)[_i]), (LAS unsigned*)(lds + (bufoff) + ldsw + _i * 8192), 16, 0, 0); } while (0)
; #define PG8_LDA(dst, b, h) do { _Pragma("unroll") for (int m = 0; m < 4; ++m) _Pragma("unroll") for (int k = 0; k < 2; ++k) dst[m][k] = *(const LAS bf16x8*)(lds + PG8_SA(b, h) + aoff + m * 2048 + k * 1024); } while (0)
; #define PG8_LDB(dst, b, h) do { _Pragma("unroll") for (int n = 0; n < 2; ++n) _Pragma("unroll") for (int k = 0; k < 2; ++k) dst[n][k] = *(const LAS bf16x8*)(lds + PG8_SB(b, h) + boff + n * 2048 + k * 1024); } while (0)
; #define PG8_MMA(ai, bj, At, Bt) do { __builtin_amdgcn_s_setprio(1); _Pragma("unroll") for (int m = 0; m < 4; ++m) _Pragma("unroll") for (int n = 0; n < 2; ++n) _Pragma("unroll") for (int k = 0; k < 2; ++k) \
;         acc[ai][bj][m][n] = __builtin_amdgcn_mfma_f32_16x16x32_bf16(Bt[n][k], At[m][k], acc[ai][bj][m][n], 0, 0, 0); __builtin_amdgcn_s_setprio(0); } while (0)
; #define PG8_WAIT_V(n) asm volatile("s_waitcnt vmcnt(" #n ")" ::: "memory")
; #define PG8_WAIT_L(n) asm volatile("s_waitcnt lgkmcnt(" #n ")" ::: "memory")
; #define PG8_BAR __builtin_amdgcn_s_barrier()
; #define PG8_SCHED __builtin_amdgcn_sched_barrier(0)
; template <class Epi>
; __device__ __forceinline__ void gemm_phase(LAS unsigned char* lds, const Gemm g, const Epi& E) {
;     ...
;             PG8_LDB(B1, 0, 1); PG8_STAGE(PG8_SB(0, 0), b2, voffB);
;             PG8_BAR; PG8_WAIT_L(0); PG8_MMA(0, 1, At, B1); PG8_BAR;
;             PG8_LDA(At, 0, 1); PG8_STAGE(PG8_SA(0, 0), a2, voffA);
;             PG8_BAR; PG8_WAIT_L(0); PG8_MMA(1, 0, At, B0); PG8_BAR; PG8_SCHED;
;             PG8_STAGE(PG8_SB(0, 1), b2 + hstepB, voffB);
;             PG8_WAIT_V(6); PG8_BAR; PG8_MMA(1, 1, At, B1); PG8_BAR;
;             PG8_LDB(B0, 1, 0); PG8_SCHED; PG8_LDA(At, 1, 0); PG8_STAGE(PG8_SA(0, 1), a2 + hstepA, voffA);
;             PG8_WAIT_L(8); PG8_BAR; PG8_WAIT_L(0); PG8_MMA(0, 0, At, B0); PG8_BAR; PG8_SCHED;
	s_waitcnt lgkmcnt(0)
	v_mfma_f32_16x16x32_bf16 v[150:153], v[192:195], v[106:109], v[150:153]
	v_mfma_f32_16x16x32_bf16 v[106:109], v[204:207], v[106:109], v[146:149]
	v_mfma_f32_16x16x32_bf16 v[122:125], v[204:207], v[130:133], v[122:125]
	v_mfma_f32_16x16x32_bf16 v[102:105], v[192:195], v[154:157], v[102:105]
	v_mfma_f32_16x16x32_bf16 v[98:101], v[204:207], v[154:157], v[98:101]
	v_mfma_f32_16x16x32_bf16 v[70:73], v[192:195], v[170:173], v[70:73]
	v_mfma_f32_16x16x32_bf16 v[66:69], v[204:207], v[170:173], v[66:69]
	v_mfma_f32_16x16x32_bf16 v[150:153], v[196:199], v[110:113], v[150:153]
	v_mfma_f32_16x16x32_bf16 v[106:109], v[226:229], v[110:113], v[106:109]
	v_mfma_f32_16x16x32_bf16 v[110:113], v[192:195], v[130:133], v[126:129]
	v_mfma_f32_16x16x32_bf16 v[122:125], v[226:229], v[134:137], v[122:125]
	v_mfma_f32_16x16x32_bf16 v[102:105], v[196:199], v[158:161], v[102:105]
	v_mfma_f32_16x16x32_bf16 v[98:101], v[226:229], v[158:161], v[98:101]
	v_mfma_f32_16x16x32_bf16 v[70:73], v[196:199], v[174:177], v[70:73]
	v_mfma_f32_16x16x32_bf16 v[66:69], v[226:229], v[174:177], v[66:69]
	v_mfma_f32_16x16x32_bf16 v[110:113], v[196:199], v[134:137], v[110:113]
	s_barrier
	ds_read_b128 v[126:129], v202 offset:16384
	ds_read_b128 v[130:133], v202 offset:17408
	ds_read_b128 v[134:137], v202 offset:18432
	ds_read_b128 v[146:149], v202 offset:19456
	ds_read_b128 v[154:157], v202 offset:20480
	ds_read_b128 v[158:161], v202 offset:21504
	ds_read_b128 v[170:173], v202 offset:22528
	ds_read_b128 v[174:177], v202 offset:23552
	global_load_lds_dwordx4 v[236:237], off
	v_lshl_add_u64 v[238:239], s[64:65], 0, v[182:183]
	s_mov_b32 m0, s25
	s_nop 0
	global_load_lds_dwordx4 v[238:239], off
	s_barrier
	s_waitcnt lgkmcnt(0)
	v_mfma_f32_16x16x32_bf16 v[62:65], v[74:77], v[126:129], v[62:65]
	v_mfma_f32_16x16x32_bf16 v[58:61], v[86:89], v[126:129], v[58:61]
	v_mfma_f32_16x16x32_bf16 v[46:49], v[74:77], v[134:137], v[46:49]
	v_mfma_f32_16x16x32_bf16 v[42:45], v[86:89], v[134:137], v[42:45]
	v_mfma_f32_16x16x32_bf16 v[30:33], v[74:77], v[154:157], v[30:33]
	v_mfma_f32_16x16x32_bf16 v[26:29], v[86:89], v[154:157], v[26:29]
	v_mfma_f32_16x16x32_bf16 v[14:17], v[74:77], v[170:173], v[14:17]
	v_mfma_f32_16x16x32_bf16 v[10:13], v[86:89], v[170:173], v[10:13]
	v_mfma_f32_16x16x32_bf16 v[62:65], v[82:85], v[130:133], v[62:65]
	v_mfma_f32_16x16x32_bf16 v[58:61], v[94:97], v[130:133], v[58:61]
	v_mfma_f32_16x16x32_bf16 v[46:49], v[82:85], v[146:149], v[46:49]
	v_mfma_f32_16x16x32_bf16 v[42:45], v[94:97], v[146:149], v[42:45]
	v_mfma_f32_16x16x32_bf16 v[30:33], v[82:85], v[158:161], v[30:33]
	v_mfma_f32_16x16x32_bf16 v[26:29], v[94:97], v[158:161], v[26:29]
	v_mfma_f32_16x16x32_bf16 v[14:17], v[82:85], v[174:177], v[14:17]
	v_mfma_f32_16x16x32_bf16 v[10:13], v[94:97], v[174:177], v[10:13]
	s_barrier
	s_add_u32 s72, s60, 0x40000
	s_addc_u32 s73, s61, 0
	s_add_i32 s74, s74, s1
	v_lshl_add_u64 v[74:75], s[72:73], 0, v[184:185]
	s_mov_b32 m0, s74
	s_nop 0
	global_load_lds_dwordx4 v[74:75], off
	v_lshl_add_u64 v[74:75], s[72:73], 0, v[180:181]
	s_add_i32 m0, s74, 0x2000
	s_nop 0
	global_load_lds_dwordx4 v[74:75], off
	s_add_i32 s72, 0, 0x18000
	v_add_u32_e32 v94, s72, v201
	s_waitcnt vmcnt(6)
	s_barrier
	v_mfma_f32_16x16x32_bf16 v[54:57], v[192:195], v[126:129], v[54:57]
	v_mfma_f32_16x16x32_bf16 v[50:53], v[204:207], v[126:129], v[50:53]
	v_mfma_f32_16x16x32_bf16 v[38:41], v[192:195], v[134:137], v[38:41]
	v_mfma_f32_16x16x32_bf16 v[34:37], v[204:207], v[134:137], v[34:37]
	v_mfma_f32_16x16x32_bf16 v[22:25], v[192:195], v[154:157], v[22:25]
	v_mfma_f32_16x16x32_bf16 v[18:21], v[204:207], v[154:157], v[18:21]
	v_mfma_f32_16x16x32_bf16 v[6:9], v[192:195], v[170:173], v[6:9]
	v_mfma_f32_16x16x32_bf16 v[2:5], v[204:207], v[170:173], v[2:5]
	v_mfma_f32_16x16x32_bf16 v[54:57], v[196:199], v[130:133], v[54:57]
	v_mfma_f32_16x16x32_bf16 v[50:53], v[226:229], v[130:133], v[50:53]
	v_mfma_f32_16x16x32_bf16 v[38:41], v[196:199], v[146:149], v[38:41]
	v_mfma_f32_16x16x32_bf16 v[34:37], v[226:229], v[146:149], v[34:37]
	v_mfma_f32_16x16x32_bf16 v[22:25], v[196:199], v[158:161], v[22:25]
	v_mfma_f32_16x16x32_bf16 v[18:21], v[226:229], v[158:161], v[18:21]
	v_mfma_f32_16x16x32_bf16 v[6:9], v[196:199], v[174:177], v[6:9]
	v_mfma_f32_16x16x32_bf16 v[2:5], v[226:229], v[174:177], v[2:5]
	s_barrier
	ds_read_b128 v[74:77], v94
	ds_read_b128 v[82:85], v94 offset:1024
	ds_read_b128 v[86:89], v94 offset:2048
	ds_read_b128 v[94:97], v94 offset:3072
	s_add_u32 s64, s64, 0x40000
	s_addc_u32 s65, s65, 0
	s_mov_b32 m0, s31
	v_lshl_add_u64 v[146:147], s[64:65], 0, v[186:187]
	ds_read_b128 v[126:129], v202 offset:32768
	ds_read_b128 v[130:133], v202 offset:33792
	ds_read_b128 v[134:137], v202 offset:34816
	ds_read_b128 v[154:157], v202 offset:35840
	ds_read_b128 v[158:161], v202 offset:36864
	ds_read_b128 v[170:173], v202 offset:37888
	ds_read_b128 v[174:177], v202 offset:38912
	ds_read_b128 v[192:195], v202 offset:39936
	global_load_lds_dwordx4 v[146:147], off
	v_lshl_add_u64 v[146:147], s[64:65], 0, v[182:183]
	s_mov_b32 m0, s36
	s_nop 0
	global_load_lds_dwordx4 v[146:147], off
	s_waitcnt lgkmcnt(8)
	s_barrier
; #define PG8_STAGE(bufoff, gbase, voff) do { _Pragma("unroll") for (int _i = 0; _i < 2; ++_i) \
;         __builtin_amdgcn_global_load_lds((const unsigned*)((const char*)(gbase) + (voff)[_i]), (LAS unsigned*)(lds + (bufoff) + ldsw + _i * 8192), 16, 0, 0); } while (0)
; #define PG8_LDA(dst, b, h) do { _Pragma("unroll") for (int m = 0; m < 4; ++m) _Pragma("unroll") for (int k = 0; k < 2; ++k) dst[m][k] = *(const LAS bf16x8*)(lds + PG8_SA(b, h) + aoff + m * 2048 + k * 1024); } while (0)
; #define PG8_LDB(dst, b, h) do { _Pragma("unroll") for (int n = 0; n < 2; ++n) _Pragma("unroll") for (int k = 0; k < 2; ++k) dst[n][k] = *(const LAS bf16x8*)(lds + PG8_SB(b, h) + boff + n * 2048 + k * 1024); } while (0)
; #define PG8_MMA(ai, bj, At, Bt) do { __builtin_amdgcn_s_setprio(1); _Pragma("unroll") for (int m = 0; m < 4; ++m) _Pragma("unroll") for (int n = 0; n < 2; ++n) _Pragma("unroll") for (int k = 0; k < 2; ++k) \
;         acc[ai][bj][m][n] = __builtin_amdgcn_mfma_f32_16x16x32_bf16(Bt[n][k], At[m][k], acc[ai][bj][m][n], 0, 0, 0); __builtin_amdgcn_s_setprio(0); } while (0)
; #define PG8_WAIT_L(n) asm volatile("s_waitcnt lgkmcnt(" #n ")" ::: "memory")
; #define PG8_BAR __builtin_amdgcn_s_barrier()
; #define PG8_SCHED __builtin_amdgcn_sched_barrier(0)
; template <class Epi>
; __device__ __forceinline__ void gemm_phase(LAS unsigned char* lds, const Gemm g, const Epi& E) {
;     ...
;             PG8_WAIT_L(8); PG8_BAR; PG8_WAIT_L(0); PG8_MMA(0, 0, At, B0); PG8_BAR; PG8_SCHED;
;             PG8_LDB(B1, 1, 1); PG8_STAGE(PG8_SB(1, 0), b3, voffB);
;             PG8_BAR; PG8_WAIT_L(0); PG8_MMA(0, 1, At, B1); PG8_BAR;
;             PG8_LDA(At, 1, 1); PG8_STAGE(PG8_SA(1, 0), a3, voffA);
;             PG8_BAR; PG8_WAIT_L(0); PG8_MMA(1, 0, At, B0); PG8_BAR; PG8_SCHED;
	s_waitcnt lgkmcnt(0)
	v_mfma_f32_16x16x32_bf16 v[146:149], v[74:77], v[126:129], v[166:169]
	v_mfma_f32_16x16x32_bf16 v[166:169], v[82:85], v[130:133], v[146:149]
	v_mfma_f32_16x16x32_bf16 v[146:149], v[86:89], v[126:129], v[162:165]
	v_mfma_f32_16x16x32_bf16 v[142:145], v[74:77], v[134:137], v[142:145]
	v_mfma_f32_16x16x32_bf16 v[138:141], v[86:89], v[134:137], v[138:141]
	v_mfma_f32_16x16x32_bf16 v[118:121], v[74:77], v[158:161], v[118:121]
	v_mfma_f32_16x16x32_bf16 v[114:117], v[86:89], v[158:161], v[114:117]
	v_mfma_f32_16x16x32_bf16 v[90:93], v[74:77], v[174:177], v[90:93]
	v_mfma_f32_16x16x32_bf16 v[78:81], v[86:89], v[174:177], v[78:81]
	v_mfma_f32_16x16x32_bf16 v[162:165], v[94:97], v[130:133], v[146:149]
	v_mfma_f32_16x16x32_bf16 v[142:145], v[82:85], v[154:157], v[142:145]
	v_mfma_f32_16x16x32_bf16 v[138:141], v[94:97], v[154:157], v[138:141]
	v_mfma_f32_16x16x32_bf16 v[118:121], v[82:85], v[170:173], v[118:121]
	v_mfma_f32_16x16x32_bf16 v[114:117], v[94:97], v[170:173], v[114:117]
	v_mfma_f32_16x16x32_bf16 v[90:93], v[82:85], v[192:195], v[90:93]
	v_mfma_f32_16x16x32_bf16 v[78:81], v[94:97], v[192:195], v[78:81]
	s_barrier
	s_add_i32 s64, 0, 0x1c000
	v_add_u32_e32 v146, s64, v201
	s_add_i32 s65, s72, s1
	ds_read_b128 v[196:199], v146
	ds_read_b128 v[204:207], v146 offset:1024
	ds_read_b128 v[226:229], v146 offset:2048
	ds_read_b128 v[230:233], v146 offset:3072
	v_lshl_add_u64 v[146:147], v[208:209], 0, s[86:87]
	s_mov_b32 m0, s65
	s_nop 0
	global_load_lds_dwordx4 v[146:147], off
	v_lshl_add_u64 v[146:147], v[234:235], 0, s[86:87]
	s_add_i32 m0, s65, 0x2000
	s_nop 0
	global_load_lds_dwordx4 v[146:147], off
	s_barrier
	s_waitcnt lgkmcnt(0)
	v_mfma_f32_16x16x32_bf16 v[146:149], v[196:199], v[126:129], v[150:153]
	v_mfma_f32_16x16x32_bf16 v[106:109], v[226:229], v[126:129], v[106:109]
	v_mfma_f32_16x16x32_bf16 v[150:153], v[204:207], v[130:133], v[146:149]
	v_mfma_f32_16x16x32_bf16 v[146:149], v[230:233], v[130:133], v[106:109]
	v_mfma_f32_16x16x32_bf16 v[106:109], v[196:199], v[134:137], v[110:113]
	v_mfma_f32_16x16x32_bf16 v[126:129], v[204:207], v[154:157], v[106:109]
	v_mfma_f32_16x16x32_bf16 v[106:109], v[226:229], v[134:137], v[122:125]
	v_mfma_f32_16x16x32_bf16 v[102:105], v[196:199], v[158:161], v[102:105]
	v_mfma_f32_16x16x32_bf16 v[98:101], v[226:229], v[158:161], v[98:101]
	v_mfma_f32_16x16x32_bf16 v[70:73], v[196:199], v[174:177], v[70:73]
	v_mfma_f32_16x16x32_bf16 v[66:69], v[226:229], v[174:177], v[66:69]
	v_mfma_f32_16x16x32_bf16 v[122:125], v[230:233], v[154:157], v[106:109]
	v_mfma_f32_16x16x32_bf16 v[102:105], v[204:207], v[170:173], v[102:105]
	v_mfma_f32_16x16x32_bf16 v[98:101], v[230:233], v[170:173], v[98:101]
	v_mfma_f32_16x16x32_bf16 v[70:73], v[204:207], v[192:195], v[70:73]
	v_mfma_f32_16x16x32_bf16 v[66:69], v[230:233], v[192:195], v[66:69]
	s_mov_b32 m0, s50
	v_lshl_add_u64 v[192:193], v[236:237], 0, s[86:87]
	s_barrier
	ds_read_b128 v[106:109], v202 offset:49152
	ds_read_b128 v[110:113], v202 offset:50176
	ds_read_b128 v[130:133], v202 offset:51200
	ds_read_b128 v[134:137], v202 offset:52224
	ds_read_b128 v[154:157], v202 offset:53248
	ds_read_b128 v[158:161], v202 offset:54272
	ds_read_b128 v[170:173], v202 offset:55296
	ds_read_b128 v[174:177], v202 offset:56320
	global_load_lds_dwordx4 v[192:193], off
	v_lshl_add_u64 v[192:193], v[238:239], 0, s[86:87]
	s_mov_b32 m0, s66
	s_nop 0
	global_load_lds_dwordx4 v[192:193], off
	s_barrier
	s_waitcnt lgkmcnt(0)
	v_mfma_f32_16x16x32_bf16 v[62:65], v[74:77], v[106:109], v[62:65]
	v_mfma_f32_16x16x32_bf16 v[58:61], v[86:89], v[106:109], v[58:61]
	v_mfma_f32_16x16x32_bf16 v[46:49], v[74:77], v[130:133], v[46:49]
	v_mfma_f32_16x16x32_bf16 v[42:45], v[86:89], v[130:133], v[42:45]
	v_mfma_f32_16x16x32_bf16 v[30:33], v[74:77], v[154:157], v[30:33]
	v_mfma_f32_16x16x32_bf16 v[26:29], v[86:89], v[154:157], v[26:29]
	v_mfma_f32_16x16x32_bf16 v[14:17], v[74:77], v[170:173], v[14:17]
	v_mfma_f32_16x16x32_bf16 v[10:13], v[86:89], v[170:173], v[10:13]
	v_mfma_f32_16x16x32_bf16 v[62:65], v[82:85], v[110:113], v[62:65]
	v_mfma_f32_16x16x32_bf16 v[58:61], v[94:97], v[110:113], v[58:61]
	v_mfma_f32_16x16x32_bf16 v[46:49], v[82:85], v[134:137], v[46:49]
	v_mfma_f32_16x16x32_bf16 v[42:45], v[94:97], v[134:137], v[42:45]
	v_mfma_f32_16x16x32_bf16 v[30:33], v[82:85], v[158:161], v[30:33]
	v_mfma_f32_16x16x32_bf16 v[26:29], v[94:97], v[158:161], v[26:29]
	v_mfma_f32_16x16x32_bf16 v[14:17], v[82:85], v[174:177], v[14:17]
	v_mfma_f32_16x16x32_bf16 v[10:13], v[94:97], v[174:177], v[10:13]
	s_barrier
; #define PG8_STAGE(bufoff, gbase, voff) do { _Pragma("unroll") for (int _i = 0; _i < 2; ++_i) \
;         __builtin_amdgcn_global_load_lds((const unsigned*)((const char*)(gbase) + (voff)[_i]), (LAS unsigned*)(lds + (bufoff) + ldsw + _i * 8192), 16, 0, 0); } while (0)
; #define PG8_MMA(ai, bj, At, Bt) do { __builtin_amdgcn_s_setprio(1); _Pragma("unroll") for (int m = 0; m < 4; ++m) _Pragma("unroll") for (int n = 0; n < 2; ++n) _Pragma("unroll") for (int k = 0; k < 2; ++k) \
;         acc[ai][bj][m][n] = __builtin_amdgcn_mfma_f32_16x16x32_bf16(Bt[n][k], At[m][k], acc[ai][bj][m][n], 0, 0, 0); __builtin_amdgcn_s_setprio(0); } while (0)
; #define PG8_WAIT_V(n) asm volatile("s_waitcnt vmcnt(" #n ")" ::: "memory")
; #define PG8_BAR __builtin_amdgcn_s_barrier()
; template <class Epi>
; __device__ __forceinline__ void gemm_phase(LAS unsigned char* lds, const Gemm g, const Epi& E) {
;     ...
;             PG8_STAGE(PG8_SB(1, 1), b3 + hstepB, voffB);
;             PG8_WAIT_V(6); PG8_BAR; PG8_MMA(1, 1, At, B1); PG8_BAR;
;         }
;     __device__ __forceinline__ void operator()(const AccT& acc, const Unit& u, int wr, int wc, int fr, int fq) const {
;     ...
;         const int gpm = mapA.src(u.pm);
;         const bool isq = u.pn < 4, isv = u.pn >= 8;
;         const bool lat = gpm >= 32 && !isv;
;         bf16_t* base = isq ? Q : (isv ? Vv + (size_t)(u.pn - 8) * 256 : Kk);
;         const int hh = isv ? 0 : (u.pn & 3);
;         const int ldo = isv ? 2048 : 1024;
;         const float osc = isq ? 0.0625f : 1.0f;
;         const int p0 = 16 * wc + 4 * fq;
;         f32x4 ctR[2][2], ctC[4][2];
;         if (lat) {
; #pragma unroll
;             for (int ai = 0; ai < 2; ++ai) { const int pr = ((gpm - 32) * 4 + 2 * ai + wr) & 31;
;                 ctR[ai][0] = *(const f32x4*)(cs + pr * 64 + p0); ctR[ai][1] = *(const f32x4*)(cs + pr * 64 + p0 + 2); }
; #pragma unroll
;             for (int m = 0; m < 4; ++m) { const int pc = m * 16 + fr;
;                 ctC[m][0] = *(const f32x4*)(cs + pc * 64 + p0); ctC[m][1] = *(const f32x4*)(cs + pc * 64 + p0 + 2); }
;         }
	s_add_u32 s60, s60, 0x40080
	s_addc_u32 s61, s61, 0
	s_add_i32 s64, s64, s1
	v_lshl_add_u64 v[74:75], s[60:61], 0, v[184:185]
	s_mov_b32 m0, s64
	s_nop 0
	global_load_lds_dwordx4 v[74:75], off
	v_lshl_add_u64 v[74:75], s[60:61], 0, v[180:181]
	s_add_i32 m0, s64, 0x2000
	s_nop 0
	global_load_lds_dwordx4 v[74:75], off
	s_add_i32 s53, s53, 2
	s_add_u32 s4, s4, 0x100
	s_addc_u32 s5, s5, 0
	s_add_u32 s15, s15, 0x100
	s_addc_u32 s52, s52, 0
	s_cmp_gt_u32 s53, 13
	s_waitcnt vmcnt(6)
	s_barrier
	v_mfma_f32_16x16x32_bf16 v[54:57], v[196:199], v[106:109], v[54:57]
	v_mfma_f32_16x16x32_bf16 v[50:53], v[226:229], v[106:109], v[50:53]
	v_mfma_f32_16x16x32_bf16 v[38:41], v[196:199], v[130:133], v[38:41]
	v_mfma_f32_16x16x32_bf16 v[34:37], v[226:229], v[130:133], v[34:37]
	v_mfma_f32_16x16x32_bf16 v[22:25], v[196:199], v[154:157], v[22:25]
	v_mfma_f32_16x16x32_bf16 v[18:21], v[226:229], v[154:157], v[18:21]
	v_mfma_f32_16x16x32_bf16 v[6:9], v[196:199], v[170:173], v[6:9]
	v_mfma_f32_16x16x32_bf16 v[2:5], v[226:229], v[170:173], v[2:5]
	v_mfma_f32_16x16x32_bf16 v[54:57], v[204:207], v[110:113], v[54:57]
	v_mfma_f32_16x16x32_bf16 v[50:53], v[230:233], v[110:113], v[50:53]
	v_mfma_f32_16x16x32_bf16 v[38:41], v[204:207], v[134:137], v[38:41]
	v_mfma_f32_16x16x32_bf16 v[34:37], v[230:233], v[134:137], v[34:37]
	v_mfma_f32_16x16x32_bf16 v[22:25], v[204:207], v[158:161], v[22:25]
	v_mfma_f32_16x16x32_bf16 v[18:21], v[230:233], v[158:161], v[18:21]
	v_mfma_f32_16x16x32_bf16 v[6:9], v[204:207], v[174:177], v[6:9]
	v_mfma_f32_16x16x32_bf16 v[2:5], v[230:233], v[174:177], v[2:5]
	s_barrier
	s_cbranch_scc0 .LBB0_331
	s_cmp_lt_i32 s10, 16
	s_cselect_b32 s4, s68, s18
	s_add_i32 s15, s10, s4
	s_cmp_lt_i32 s11, 8
	s_cselect_b64 s[60:61], -1, 0
	s_cmp_gt_i32 s15, 31
	s_cselect_b64 s[4:5], -1, 0
	s_and_b64 s[52:53], s[60:61], s[4:5]
	v_cndmask_b32_e64 v74, 0, 1, s[52:53]
	v_mov_b32_e32 v194, v200
	v_mov_b32_e32 v193, v1
	v_cmp_ne_u32_e64 s[4:5], 1, v74
	s_andn2_b64 vcc, exec, s[52:53]
	s_cbranch_vccnz .LBB0_334
	v_lshl_add_u32 v74, v193, 2, s67
	v_readlane_b32 s52, v254, 2
	s_lshl_b32 s15, s15, 8
	v_ashrrev_i32_e32 v75, 31, v74
	v_readlane_b32 s53, v254, 3
	s_add_i32 s15, s15, s44
	s_nop 0
	v_lshl_add_u64 v[74:75], v[74:75], 3, s[52:53]
	s_and_b32 s52, s15, 0x7c0
	s_addk_i32 s15, 0x80
	s_lshl_b32 s76, s52, 3
	s_and_b32 s15, s15, 0x7c0
	v_lshl_add_u64 v[76:77], v[74:75], 0, s[76:77]
	s_lshl_b32 s76, s15, 3
	global_load_dwordx4 v[170:173], v[76:77], off offset:16
	global_load_dwordx4 v[174:177], v[76:77], off
	v_lshl_add_u64 v[76:77], v[74:75], 0, s[76:77]
	global_load_dwordx4 v[86:89], v[76:77], off offset:16
	global_load_dwordx4 v[94:97], v[76:77], off
	v_lshlrev_b32_e32 v76, 6, v194
	v_ashrrev_i32_e32 v77, 31, v76
	v_lshl_add_u64 v[82:83], v[76:77], 3, v[74:75]
	global_load_dwordx4 v[154:157], v[82:83], off offset:16
	global_load_dwordx4 v[158:161], v[82:83], off
	v_add_u32_e32 v82, 0x400, v76
	v_ashrrev_i32_e32 v83, 31, v82
	v_lshl_add_u64 v[82:83], v[82:83], 3, v[74:75]
	global_load_dwordx4 v[130:133], v[82:83], off offset:16
	global_load_dwordx4 v[134:137], v[82:83], off
	v_add_u32_e32 v82, 0x800, v76
	v_ashrrev_i32_e32 v83, 31, v82
	v_add_u32_e32 v76, 0xc00, v76
	v_lshl_add_u64 v[82:83], v[82:83], 3, v[74:75]
	v_ashrrev_i32_e32 v77, 31, v76
	global_load_dwordx4 v[106:109], v[82:83], off offset:16
	global_load_dwordx4 v[110:113], v[82:83], off
	v_lshl_add_u64 v[82:83], v[76:77], 3, v[74:75]
	global_load_dwordx4 v[74:77], v[82:83], off offset:16
	s_nop 0
	global_load_dwordx4 v[82:85], v[82:83], off

; template <class Epi>
; __device__ __forceinline__ void gemm_phase(LAS unsigned char* lds, const Gemm g, const Epi& E) {
;     ...
; #pragma unroll
;         for (int a = 0; a < 2; ++a)
; #pragma unroll
;             for (int b = 0; b < 2; ++b)
; #pragma unroll
;                 for (int m = 0; m < 4; ++m)
; #pragma unroll
;                     for (int n = 0; n < 2; ++n) acc[a][b][m][n] = (f32x4){0.f, 0.f, 0.f, 0.f};
;         cur = nxt; cA = nA; cB = nB; ++ui;
.LBB0_474:
	s_ashr_i32 s9, s8, 31
	s_lshl_b64 s[28:29], s[8:9], 19
	v_readlane_b32 s9, v255, 28
	s_add_u32 s9, s9, s28
	v_readlane_b32 s28, v255, 29
	s_addc_u32 s28, s28, s29
	s_and_b64 s[4:5], s[4:5], exec
	s_cselect_b32 s5, s28, s17
	s_cselect_b32 s4, s9, s16
	s_add_u32 s14, s14, 0x40080
	s_addc_u32 s15, s15, 0
	s_add_u32 s9, s16, 0x100
	v_mov_b32_e32 v2, 0
	s_addc_u32 s53, s17, 0
	s_mov_b32 s65, -2
	v_mov_b32_e32 v3, v2
	v_mov_b32_e32 v4, v2
	v_mov_b32_e32 v5, v2
	v_mov_b32_e32 v6, v2
	v_mov_b32_e32 v7, v2
	v_mov_b32_e32 v8, v2
	v_mov_b32_e32 v9, v2
	v_mov_b32_e32 v18, v2
	v_mov_b32_e32 v19, v2
	v_mov_b32_e32 v20, v2
	v_mov_b32_e32 v21, v2
	v_mov_b32_e32 v22, v2
	v_mov_b32_e32 v23, v2
	v_mov_b32_e32 v24, v2
	v_mov_b32_e32 v25, v2
	v_mov_b32_e32 v34, v2
	v_mov_b32_e32 v35, v2
	v_mov_b32_e32 v36, v2
	v_mov_b32_e32 v37, v2
	v_mov_b32_e32 v38, v2
	v_mov_b32_e32 v39, v2
	v_mov_b32_e32 v40, v2
	v_mov_b32_e32 v41, v2
	v_mov_b32_e32 v50, v2
	v_mov_b32_e32 v51, v2
	v_mov_b32_e32 v52, v2
	v_mov_b32_e32 v53, v2
	v_mov_b32_e32 v54, v2
	v_mov_b32_e32 v55, v2
	v_mov_b32_e32 v56, v2
	v_mov_b32_e32 v57, v2
	v_mov_b32_e32 v10, v2
	v_mov_b32_e32 v11, v2
	v_mov_b32_e32 v12, v2
	v_mov_b32_e32 v13, v2
	v_mov_b32_e32 v14, v2
	v_mov_b32_e32 v15, v2
	v_mov_b32_e32 v16, v2
	v_mov_b32_e32 v17, v2
	v_mov_b32_e32 v26, v2
	v_mov_b32_e32 v27, v2
	v_mov_b32_e32 v28, v2
	v_mov_b32_e32 v29, v2
	v_mov_b32_e32 v30, v2
	v_mov_b32_e32 v31, v2
	v_mov_b32_e32 v32, v2
	v_mov_b32_e32 v33, v2
	v_mov_b32_e32 v42, v2
	v_mov_b32_e32 v43, v2
	v_mov_b32_e32 v44, v2
	v_mov_b32_e32 v45, v2
	v_mov_b32_e32 v46, v2
	v_mov_b32_e32 v47, v2
	v_mov_b32_e32 v48, v2
	v_mov_b32_e32 v49, v2
	v_mov_b32_e32 v58, v2
	v_mov_b32_e32 v59, v2
	v_mov_b32_e32 v60, v2
	v_mov_b32_e32 v61, v2
	v_mov_b32_e32 v62, v2
	v_mov_b32_e32 v63, v2
	v_mov_b32_e32 v64, v2
	v_mov_b32_e32 v65, v2
	v_mov_b32_e32 v74, v2
	v_mov_b32_e32 v75, v2
	v_mov_b32_e32 v76, v2
	v_mov_b32_e32 v77, v2
	v_mov_b32_e32 v78, v2
	v_mov_b32_e32 v79, v2
	v_mov_b32_e32 v80, v2
	v_mov_b32_e32 v81, v2
	v_mov_b32_e32 v98, v2
	v_mov_b32_e32 v99, v2
	v_mov_b32_e32 v100, v2
	v_mov_b32_e32 v101, v2
	v_mov_b32_e32 v102, v2
	v_mov_b32_e32 v103, v2
	v_mov_b32_e32 v104, v2
	v_mov_b32_e32 v105, v2
	v_mov_b32_e32 v114, v2
	v_mov_b32_e32 v115, v2
	v_mov_b32_e32 v116, v2
	v_mov_b32_e32 v117, v2
	v_mov_b32_e32 v118, v2
	v_mov_b32_e32 v119, v2
	v_mov_b32_e32 v120, v2
	v_mov_b32_e32 v121, v2
	v_mov_b32_e32 v130, v2
	v_mov_b32_e32 v131, v2
	v_mov_b32_e32 v132, v2
	v_mov_b32_e32 v133, v2
	v_mov_b32_e32 v134, v2
	v_mov_b32_e32 v135, v2
	v_mov_b32_e32 v136, v2
	v_mov_b32_e32 v137, v2
	v_mov_b32_e32 v90, v2
	v_mov_b32_e32 v91, v2
	v_mov_b32_e32 v92, v2
	v_mov_b32_e32 v93, v2
	v_mov_b32_e32 v94, v2
	v_mov_b32_e32 v95, v2
	v_mov_b32_e32 v96, v2
	v_mov_b32_e32 v97, v2
	v_mov_b32_e32 v106, v2
	v_mov_b32_e32 v107, v2
	v_mov_b32_e32 v108, v2
	v_mov_b32_e32 v109, v2
	v_mov_b32_e32 v110, v2
	v_mov_b32_e32 v111, v2
	v_mov_b32_e32 v112, v2
	v_mov_b32_e32 v113, v2
	v_mov_b32_e32 v122, v2
	v_mov_b32_e32 v123, v2
	v_mov_b32_e32 v124, v2
	v_mov_b32_e32 v125, v2
	v_mov_b32_e32 v126, v2
	v_mov_b32_e32 v127, v2
	v_mov_b32_e32 v128, v2
	v_mov_b32_e32 v129, v2
	v_mov_b32_e32 v138, v2
	v_mov_b32_e32 v139, v2
	v_mov_b32_e32 v140, v2
	v_mov_b32_e32 v141, v2
	v_mov_b32_e32 v142, v2
	v_mov_b32_e32 v143, v2
	v_mov_b32_e32 v144, v2
	v_mov_b32_e32 v145, v2
	s_nop 0
	s_nop 0
	s_nop 0
	s_nop 0
